# v54 + MLA steady step: row-sum tail adds, exit compare and the next step's K-fragment addresses computed before the end-of-step barrier
# speedup vs baseline: 1.0006x; 1.0006x over previous
.Lmla2_reads:
	ds_read_b128 v[82:85], v67
	ds_read_b128 v[158:161], v67 offset:2048
	ds_read_b128 v[162:165], v66
	ds_read_b128 v[150:153], v66 offset:2048
	ds_read_b128 v[146:149], v67 offset:4096
	ds_read_b128 v[142:145], v67 offset:6144
	ds_read_b128 v[138:141], v66 offset:4096
	ds_read_b128 v[134:137], v66 offset:6144
	ds_read_b128 v[130:133], v67 offset:8192
	ds_read_b128 v[126:129], v67 offset:10240
	ds_read_b128 v[122:125], v66 offset:8192
	ds_read_b128 v[154:157], v66 offset:10240
	s_waitcnt lgkmcnt(11)
	v_mfma_f32_32x32x16_bf16 v[66:81], v[82:85], v[98:101], v[50:65]
	s_lshl_b32 s58, s49, 13
	s_waitcnt lgkmcnt(10)
	v_mfma_f32_32x32x16_bf16 v[82:97], v[158:161], v[98:101], v[50:65]
	v_add_u32_e32 v158, s58, v183
	s_add_u32 s26, s54, s24
	s_addc_u32 s27, s55, s25
	s_xor_b32 s57, s49, 1
	s_mul_i32 s56, s57, 0x3000
	s_add_i32 s51, s56, s38
	s_mov_b32 s98, m0
	s_mov_b32 m0, s51
	s_nop 0
	global_load_lds_dwordx4 v1, s[26:27]
	s_mov_b32 m0, s98
	s_and_b64 vcc, exec, s[8:9]
	s_cbranch_vccnz .LBB0_1478
	s_add_i32 s26, s56, s39
	s_mov_b32 s27, m0
	s_mov_b32 m0, s26
	s_nop 0
	global_load_lds_dwordx4 v180, s[22:23]
	s_mov_b32 m0, s27

.LBB0_1482:
	v_exp_f32_e32 v66, v66
	v_exp_f32_e32 v67, v67
	v_exp_f32_e32 v68, v68
	v_exp_f32_e32 v69, v69
	v_exp_f32_e32 v70, v70
	v_exp_f32_e32 v71, v71
	v_exp_f32_e32 v72, v72
	v_exp_f32_e32 v73, v73
	v_pk_add_f32 v[154:155], v[66:67], v[68:69]
	v_pk_add_f32 v[156:157], v[70:71], v[72:73]
	v_pk_add_f32 v[158:159], v[154:155], v[156:157]
	v_cvt_pk_bf16_f32 v66, v66, v67
	v_cvt_pk_bf16_f32 v67, v68, v69
	v_cvt_pk_bf16_f32 v68, v70, v71
	v_cvt_pk_bf16_f32 v69, v72, v73
	v_exp_f32_e32 v74, v74
	v_exp_f32_e32 v75, v75
	v_mfma_f32_32x32x16_bf16 v[18:33], v[66:69], v[150:153], v[18:33]
	v_exp_f32_e32 v76, v76
	v_exp_f32_e32 v77, v77
	v_exp_f32_e32 v78, v78
	s_waitcnt lgkmcnt(6)
	v_mfma_f32_32x32x16_bf16 v[34:49], v[66:69], v[134:137], v[34:49]
	v_exp_f32_e32 v79, v79
	v_exp_f32_e32 v80, v80
	v_exp_f32_e32 v81, v81
	v_pk_add_f32 v[154:155], v[74:75], v[76:77]
	v_pk_add_f32 v[156:157], v[78:79], v[80:81]
	v_pk_add_f32 v[160:161], v[154:155], v[156:157]
	v_cvt_pk_bf16_f32 v70, v74, v75
	v_cvt_pk_bf16_f32 v71, v76, v77
	v_cvt_pk_bf16_f32 v72, v78, v79
	v_cvt_pk_bf16_f32 v73, v80, v81
	v_exp_f32_e32 v82, v82
	v_exp_f32_e32 v83, v83
	v_mfma_f32_32x32x16_bf16 v[18:33], v[70:73], v[146:149], v[18:33]
	v_exp_f32_e32 v84, v84
	v_exp_f32_e32 v85, v85
	v_exp_f32_e32 v86, v86
	s_waitcnt lgkmcnt(4)
	v_mfma_f32_32x32x16_bf16 v[34:49], v[70:73], v[130:133], v[34:49]
	v_exp_f32_e32 v87, v87
	v_exp_f32_e32 v88, v88
	v_exp_f32_e32 v89, v89
	v_pk_add_f32 v[154:155], v[82:83], v[84:85]
	v_pk_add_f32 v[156:157], v[86:87], v[88:89]
	v_pk_add_f32 v[162:163], v[154:155], v[156:157]
	v_cvt_pk_bf16_f32 v74, v82, v83
	v_cvt_pk_bf16_f32 v75, v84, v85
	v_cvt_pk_bf16_f32 v76, v86, v87
	v_cvt_pk_bf16_f32 v77, v88, v89
	v_exp_f32_e32 v90, v90
	v_exp_f32_e32 v91, v91
	v_mfma_f32_32x32x16_bf16 v[18:33], v[74:77], v[142:145], v[18:33]
	v_exp_f32_e32 v92, v92
	v_exp_f32_e32 v93, v93
	v_exp_f32_e32 v94, v94
	s_waitcnt lgkmcnt(2)
	v_mfma_f32_32x32x16_bf16 v[34:49], v[74:77], v[126:129], v[34:49]
	v_exp_f32_e32 v95, v95
	v_exp_f32_e32 v96, v96
	v_exp_f32_e32 v97, v97
	v_pk_add_f32 v[154:155], v[90:91], v[92:93]
	v_pk_add_f32 v[156:157], v[94:95], v[96:97]
	v_pk_add_f32 v[164:165], v[154:155], v[156:157]
	v_cvt_pk_bf16_f32 v78, v90, v91
	v_cvt_pk_bf16_f32 v79, v92, v93
	v_cvt_pk_bf16_f32 v80, v94, v95
	v_cvt_pk_bf16_f32 v81, v96, v97
	v_pk_add_f32 v[158:159], v[158:159], v[160:161]
	s_add_u32 s24, s24, 0x10000
	s_addc_u32 s25, s25, 0
	v_mfma_f32_32x32x16_bf16 v[18:33], v[78:81], v[138:141], v[18:33]
	v_pk_add_f32 v[162:163], v[162:163], v[164:165]
	s_add_u32 s22, s22, 0x1000
	s_addc_u32 s23, s23, 0
	s_waitcnt lgkmcnt(0)
	v_mfma_f32_32x32x16_bf16 v[34:49], v[78:81], v[122:125], v[34:49]
	v_pk_add_f32 v[158:159], v[158:159], v[162:163]
	v_add_f32_e32 v158, v158, v159
	v_add_u32_e32 v66, s56, v182
	v_add_f32_e32 v173, v173, v158
	v_add_u32_e32 v67, v66, v184
	v_add_u32_e32 v66, v66, v189
	s_cmp_eq_u32 s24, 0x200000
	s_waitcnt vmcnt(0) lgkmcnt(0)
	s_barrier
	s_cbranch_scc1 .LBB0_1484
	s_mov_b32 s49, s57
	s_mul_i32 s52, s49, 0x3000
	s_branch .Lmla2_reads
